# grid barrier: no s_sleep between polls of the generation word
# speedup vs baseline: 1.0034x; 1.0034x over previous
.LBB0_827:
	s_and_b32 s18, s20, 0xff
	s_mov_b64 s[16:17], -1
	s_cmp_lg_u32 s18, 0
	s_mov_b64 s[22:23], -1
	s_nop 0
	s_cbranch_scc0 .LBB0_830
	s_and_b64 vcc, exec, s[22:23]
	s_cbranch_vccz .LBB0_826

.LBB0_844:
	s_and_b32 s16, s20, 0xff
	s_mov_b64 s[14:15], -1
	s_cmp_lg_u32 s16, 0
	s_mov_b64 s[18:19], -1
	s_nop 0
	s_cbranch_scc0 .LBB0_847
	s_and_b64 vcc, exec, s[18:19]
	s_cbranch_vccz .LBB0_843
